# P2 skinny split-K task: all 33 fragment loads of the wave issued up front with counted waits (was about one k-step ahead, 8-10 dependent round trips)
# baseline (speedup 1.0000x reference)
; template <class EpiS>
; __device__ __forceinline__ void sgemm_phase(LAS unsigned char* lds, const bf16* A, const bf16* Bt, int N, int K, const EpiS& E, int bidx, int nb) {
;     ...
;     for (int task = bidx; task < ntask; task += nb) {
;         const int ct = task >> 2, rt = task & 3;
;         const bf16* ap0 = A + (size_t)(rt * 32 + li) * K + wave * kper + 8 * lq; const bf16* ap1 = ap0 + (size_t)16 * K;
;         const bf16* bp = Bt + (size_t)(ct * 16 + li) * K + wave * kper + 8 * lq;
;         f32x4 acc0 = (f32x4){0.f, 0.f, 0.f, 0.f}, acc1 = acc0;
; #pragma unroll 4
;         for (int k = 0; k < kper; k += 32) { const bf16x8 b = *(const bf16x8*)(bp + k), a0 = *(const bf16x8*)(ap0 + k), a1 = *(const bf16x8*)(ap1 + k);
;             acc0 = __builtin_amdgcn_mfma_f32_16x16x32_bf16(a0, b, acc0, 0, 0, 0); acc1 = __builtin_amdgcn_mfma_f32_16x16x32_bf16(a1, b, acc1, 0, 0, 0); }
; #pragma unroll
;         for (int r = 0; r < 4; ++r) { red[wave * 512 + (4 * lq + r) * 16 + li] = acc0[r]; red[wave * 512 + (16 + 4 * lq + r) * 16 + li] = acc1[r]; }
;         __syncthreads();
;         float v = 0.f;
; #pragma unroll
;         for (int w = 0; w < 8; ++w) v += red[w * 512 + tid];
;         E(rt * 32 + (tid >> 4), ct * 16 + (tid & 15), v);
;         __syncthreads();
;     }
.LBB0_252:
	s_and_b32 s17, s3, 0x60
	v_or_b32_e32 v0, s17, v156
	v_mul_u32_u24_e32 v0, 0xb00, v0
	v_and_or_b32 v42, s0, -16, v156
	v_lshlrev_b32_e32 v0, 1, v0
	v_mad_i64_i32 v[44:45], s[18:19], v42, s15, v[4:5]
	v_lshl_add_u64 v[46:47], v[2:3], 0, v[0:1]
	v_add_co_u32_e32 v48, vcc, 0x16000, v46
	v_ashrrev_i32_e32 v43, 31, v42
	s_nop 0
	v_addc_co_u32_e32 v49, vcc, 0, v47, vcc
	v_add_lshl_u32 v0, s17, v6, 10
	s_add_i32 s16, s16, s88
	s_add_i32 s0, s0, s1
	s_add_i32 s3, s3, s14
	s_cmpk_lt_i32 s16, 0x100
	global_load_dwordx4 v[60:63], v[44:45], off
	global_load_dwordx4 v[104:107], v[46:47], off
	global_load_dwordx4 v[160:163], v[48:49], off
	global_load_dwordx4 v[64:67], v[44:45], off offset:64
	global_load_dwordx4 v[108:111], v[46:47], off offset:64
	global_load_dwordx4 v[164:167], v[48:49], off offset:64
	global_load_dwordx4 v[68:71], v[44:45], off offset:128
	global_load_dwordx4 v[112:115], v[46:47], off offset:128
	global_load_dwordx4 v[168:171], v[48:49], off offset:128
	global_load_dwordx4 v[72:75], v[44:45], off offset:192
	global_load_dwordx4 v[116:119], v[46:47], off offset:192
	global_load_dwordx4 v[172:175], v[48:49], off offset:192
	global_load_dwordx4 v[76:79], v[44:45], off offset:256
	global_load_dwordx4 v[120:123], v[46:47], off offset:256
	global_load_dwordx4 v[176:179], v[48:49], off offset:256
	global_load_dwordx4 v[80:83], v[44:45], off offset:320
	global_load_dwordx4 v[124:127], v[46:47], off offset:320
	global_load_dwordx4 v[180:183], v[48:49], off offset:320
	global_load_dwordx4 v[84:87], v[44:45], off offset:384
	global_load_dwordx4 v[128:131], v[46:47], off offset:384
	global_load_dwordx4 v[184:187], v[48:49], off offset:384
	global_load_dwordx4 v[88:91], v[44:45], off offset:448
	global_load_dwordx4 v[132:135], v[46:47], off offset:448
	global_load_dwordx4 v[188:191], v[48:49], off offset:448
	global_load_dwordx4 v[92:95], v[44:45], off offset:512
	global_load_dwordx4 v[136:139], v[46:47], off offset:512
	global_load_dwordx4 v[192:195], v[48:49], off offset:512
	global_load_dwordx4 v[96:99], v[44:45], off offset:576
	global_load_dwordx4 v[140:143], v[46:47], off offset:576
	global_load_dwordx4 v[196:199], v[48:49], off offset:576
	global_load_dwordx4 v[100:103], v[44:45], off offset:640
	global_load_dwordx4 v[144:147], v[46:47], off offset:640
	global_load_dwordx4 v[200:203], v[48:49], off offset:640
	s_waitcnt vmcnt(30)
	v_mfma_f32_16x16x32_bf16 v[14:17], v[104:107], v[60:63], 0
	v_mfma_f32_16x16x32_bf16 v[10:13], v[160:163], v[60:63], 0
	s_waitcnt vmcnt(27)
	v_mfma_f32_16x16x32_bf16 v[14:17], v[108:111], v[64:67], v[14:17]
	v_mfma_f32_16x16x32_bf16 v[10:13], v[164:167], v[64:67], v[10:13]
	s_waitcnt vmcnt(24)
	v_mfma_f32_16x16x32_bf16 v[14:17], v[112:115], v[68:71], v[14:17]
	v_mfma_f32_16x16x32_bf16 v[10:13], v[168:171], v[68:71], v[10:13]
	s_waitcnt vmcnt(21)
	v_mfma_f32_16x16x32_bf16 v[14:17], v[116:119], v[72:75], v[14:17]
	v_mfma_f32_16x16x32_bf16 v[10:13], v[172:175], v[72:75], v[10:13]
	s_waitcnt vmcnt(18)
	v_mfma_f32_16x16x32_bf16 v[14:17], v[120:123], v[76:79], v[14:17]
	v_mfma_f32_16x16x32_bf16 v[10:13], v[176:179], v[76:79], v[10:13]
	s_waitcnt vmcnt(15)
	v_mfma_f32_16x16x32_bf16 v[14:17], v[124:127], v[80:83], v[14:17]
	v_mfma_f32_16x16x32_bf16 v[10:13], v[180:183], v[80:83], v[10:13]
	s_waitcnt vmcnt(12)
	v_mfma_f32_16x16x32_bf16 v[14:17], v[128:131], v[84:87], v[14:17]
	v_mfma_f32_16x16x32_bf16 v[10:13], v[184:187], v[84:87], v[10:13]
	s_waitcnt vmcnt(9)
	v_mfma_f32_16x16x32_bf16 v[14:17], v[132:135], v[88:91], v[14:17]
	v_mfma_f32_16x16x32_bf16 v[10:13], v[188:191], v[88:91], v[10:13]
	s_waitcnt vmcnt(6)
	v_mfma_f32_16x16x32_bf16 v[14:17], v[136:139], v[92:95], v[14:17]
	v_mfma_f32_16x16x32_bf16 v[10:13], v[192:195], v[92:95], v[10:13]
	s_waitcnt vmcnt(3)
	v_mfma_f32_16x16x32_bf16 v[14:17], v[140:143], v[96:99], v[14:17]
	v_mfma_f32_16x16x32_bf16 v[10:13], v[196:199], v[96:99], v[10:13]
	s_waitcnt vmcnt(0)
	v_mfma_f32_16x16x32_bf16 v[14:17], v[144:147], v[100:103], v[14:17]
	v_lshl_add_u64 v[18:19], v[0:1], 0, v[42:43]
	v_lshlrev_b64 v[18:19], 2, v[18:19]
	v_lshl_add_u64 v[20:21], s[6:7], 0, v[18:19]
	v_mfma_f32_16x16x32_bf16 v[10:13], v[200:203], v[100:103], v[10:13]
	s_nop 3
	ds_write2_b32 v8, v14, v15 offset1:16
	ds_write2_b32 v8, v16, v17 offset0:32 offset1:48
	s_nop 1
	ds_write2_b32 v9, v10, v11 offset1:16
	ds_write2_b32 v9, v12, v13 offset0:32 offset1:48
	s_waitcnt lgkmcnt(0)
	s_barrier
	global_load_dword v10, v[20:21], off
	v_lshl_add_u64 v[12:13], s[10:11], 0, v[18:19]
	ds_read2st64_b32 v[14:15], v7 offset1:8
	ds_read2st64_b32 v[16:17], v7 offset0:16 offset1:24
	ds_read2st64_b32 v[18:19], v7 offset0:32 offset1:40
	ds_read2st64_b32 v[20:21], v7 offset0:48 offset1:56
	s_waitcnt lgkmcnt(3)
	v_add_f32_e32 v0, 0, v14
	v_add_f32_e32 v0, v0, v15
	s_waitcnt lgkmcnt(2)
	v_add_f32_e32 v0, v0, v16
	v_add_f32_e32 v0, v0, v17
	s_waitcnt lgkmcnt(1)
	v_add_f32_e32 v0, v0, v18
	v_add_f32_e32 v0, v0, v19
	s_waitcnt lgkmcnt(0)
	v_add_f32_e32 v0, v0, v20
	v_add_f32_e32 v11, v0, v21
	s_waitcnt vmcnt(0)
	v_pk_mul_f32 v[10:11], v[10:11], s[12:13]
	s_nop 0
	v_add_f32_e32 v0, v10, v11
	global_store_dword v[12:13], v0, off
	s_barrier
	s_cbranch_scc1 .LBB0_252
